# final sample-row tail (workgroups 0..15, the last to finish): XS row and final-gain pieces loaded right after grid barrier 6 instead of behind the y stores; serial load/wait/store ladder at the kernel
# speedup vs baseline: 1.0260x; 1.0044x over previous
.LBB0_972:
	s_or_b64 exec, exec, s[2:3]
	s_waitcnt lgkmcnt(0)
	v_lshl_add_u64 v[0:1], s[0:1], 0, v[174:175]
	s_barrier
	v_lshl_add_u32 v209, s92, 3, v190
	v_cmp_gt_i32_e32 vcc, 0x80, v209
	s_and_saveexec_b64 s[98:99], vcc
	s_cbranch_execz .Lsr_skip
	v_lshlrev_b32_e32 v212, 12, v209
	v_lshl_add_u32 v212, v191, 4, v212
	v_add_u32_e32 v212, 0xeec8000, v212
	global_load_dwordx4 v[216:219], v212, s[78:79] offset:1024
	global_load_dwordx4 v[220:223], v212, s[78:79] offset:2048
	global_load_dwordx4 v[224:227], v212, s[78:79]
	global_load_dwordx4 v[228:231], v212, s[78:79] offset:3072
	v_lshlrev_b32_e32 v213, 4, v191
	global_load_dwordx4 v[236:239], v213, s[90:91]
	global_load_dwordx4 v[240:243], v213, s[90:91] offset:1024
	global_load_dwordx4 v[244:247], v213, s[90:91] offset:2048
	global_load_dwordx4 v[248:251], v213, s[90:91] offset:3072
.Lsr_skip:
	s_mov_b64 exec, s[98:99]
	global_load_dwordx4 v[136:139], v[0:1], off
	global_load_dwordx4 v[140:143], v[0:1], off offset:16
	global_load_dwordx4 v[192:195], v[0:1], off offset:32
	global_load_dwordx4 v[196:199], v[0:1], off offset:48
	v_lshl_add_u64 v[0:1], s[90:91], 0, v[144:145]
	global_load_dwordx4 v[12:15], v[0:1], off
	global_load_dwordx4 v[8:11], v[0:1], off offset:64
	global_load_dwordx4 v[4:7], v[0:1], off offset:512
	s_nop 0
	global_load_dwordx4 v[0:3], v[0:1], off offset:576
	v_mov_b32_e32 v134, 0x358637bd
	s_mov_b32 s2, 0x800000
	s_waitcnt vmcnt(6)
	v_pk_add_f32 v[138:139], v[138:139], v[142:143]
	v_pk_add_f32 v[136:137], v[136:137], v[140:141]
	s_waitcnt vmcnt(4)
	v_pk_add_f32 v[140:141], v[194:195], v[198:199]
	v_pk_add_f32 v[142:143], v[192:193], v[196:197]
	v_pk_add_f32 v[138:139], v[138:139], v[140:141]
	v_pk_add_f32 v[136:137], v[136:137], v[142:143]
	s_nop 0
	v_pk_mov_b32 v[140:141], v[136:137], v[138:139] op_sel:[1,0]
	v_mov_b32_e32 v137, v139
	v_pk_add_f32 v[136:137], v[140:141], v[136:137]
	v_lshl_add_u64 v[138:139], s[0:1], 0, v[176:177]
	v_add_f32_e32 v135, v136, v137
	v_fmamk_f32 v135, v135, 0x3a800000, v134
	v_mul_f32_e32 v136, 0x4b800000, v135
	v_cmp_gt_f32_e32 vcc, s2, v135
	s_nop 1
	v_cndmask_b32_e32 v135, v135, v136, vcc
	v_rsq_f32_e32 v135, v135
	v_lshl_add_u64 v[136:137], s[76:77], 0, v[146:147]
	v_lshl_add_u64 v[136:137], v[136:137], 0, v[144:145]
	v_mul_f32_e32 v140, 0x45800000, v135
	v_cndmask_b32_e32 v140, v135, v140, vcc
	v_pk_mul_f32 v[124:125], v[124:125], v[140:141] op_sel_hi:[1,0]
	v_pk_mul_f32 v[126:127], v[126:127], v[140:141] op_sel_hi:[1,0]
	v_pk_mul_f32 v[120:121], v[120:121], v[140:141] op_sel_hi:[1,0]
	v_pk_mul_f32 v[122:123], v[122:123], v[140:141] op_sel_hi:[1,0]
	v_pk_mul_f32 v[142:143], v[116:117], v[140:141] op_sel_hi:[1,0]
	v_pk_mul_f32 v[146:147], v[118:119], v[140:141] op_sel_hi:[1,0]
	v_pk_mul_f32 v[174:175], v[112:113], v[140:141] op_sel_hi:[1,0]
	v_pk_mul_f32 v[140:141], v[114:115], v[140:141] op_sel_hi:[1,0]
	s_waitcnt vmcnt(3)
	v_pk_mul_f32 v[114:115], v[14:15], v[126:127]
	v_pk_mul_f32 v[112:113], v[12:13], v[124:125]
	s_waitcnt vmcnt(2)
	v_pk_mul_f32 v[118:119], v[10:11], v[122:123]
	v_pk_mul_f32 v[116:117], v[8:9], v[120:121]
	s_waitcnt vmcnt(1)
	v_pk_mul_f32 v[122:123], v[6:7], v[146:147]
	v_pk_mul_f32 v[120:121], v[4:5], v[142:143]
	s_waitcnt vmcnt(0)
	v_pk_mul_f32 v[126:127], v[2:3], v[140:141]
	v_pk_mul_f32 v[124:125], v[0:1], v[174:175]
	global_store_dwordx4 v[136:137], v[112:115], off
	global_store_dwordx4 v[136:137], v[116:119], off offset:64
	global_store_dwordx4 v[136:137], v[120:123], off offset:512
	global_store_dwordx4 v[136:137], v[124:127], off offset:576
	global_load_dwordx4 v[112:115], v[138:139], off
	s_nop 0
	global_load_dwordx4 v[116:119], v[138:139], off offset:16
	global_load_dwordx4 v[120:123], v[138:139], off offset:32
	global_load_dwordx4 v[124:127], v[138:139], off offset:48
	s_waitcnt vmcnt(2)
	v_pk_add_f32 v[114:115], v[114:115], v[118:119]
	v_pk_add_f32 v[112:113], v[112:113], v[116:117]
	s_waitcnt vmcnt(0)
	v_pk_add_f32 v[116:117], v[122:123], v[126:127]
	v_pk_add_f32 v[118:119], v[120:121], v[124:125]
	v_pk_add_f32 v[114:115], v[114:115], v[116:117]
	v_pk_add_f32 v[112:113], v[112:113], v[118:119]
	s_nop 0
	v_pk_mov_b32 v[116:117], v[112:113], v[114:115] op_sel:[1,0]
	v_mov_b32_e32 v113, v115
	v_pk_add_f32 v[112:113], v[116:117], v[112:113]
	v_lshl_add_u64 v[114:115], s[0:1], 0, v[178:179]
	v_add_f32_e32 v112, v112, v113
	v_fmamk_f32 v112, v112, 0x3a800000, v134
	v_mul_f32_e32 v113, 0x4b800000, v112
	v_cmp_gt_f32_e32 vcc, s2, v112
	s_nop 1
	v_cndmask_b32_e32 v112, v112, v113, vcc
	v_rsq_f32_e32 v116, v112
	v_lshl_add_u64 v[112:113], s[76:77], 0, v[148:149]
	v_lshl_add_u64 v[112:113], v[112:113], 0, v[144:145]
	v_mul_f32_e32 v117, 0x45800000, v116
	v_cndmask_b32_e32 v116, v116, v117, vcc
	v_pk_mul_f32 v[108:109], v[108:109], v[116:117] op_sel_hi:[1,0]
	v_pk_mul_f32 v[110:111], v[110:111], v[116:117] op_sel_hi:[1,0]
	v_pk_mul_f32 v[104:105], v[104:105], v[116:117] op_sel_hi:[1,0]
	v_pk_mul_f32 v[106:107], v[106:107], v[116:117] op_sel_hi:[1,0]
	v_pk_mul_f32 v[118:119], v[100:101], v[116:117] op_sel_hi:[1,0]
	v_pk_mul_f32 v[120:121], v[102:103], v[116:117] op_sel_hi:[1,0]
	v_pk_mul_f32 v[122:123], v[96:97], v[116:117] op_sel_hi:[1,0]
	v_pk_mul_f32 v[116:117], v[98:99], v[116:117] op_sel_hi:[1,0]
	v_pk_mul_f32 v[98:99], v[14:15], v[110:111]
	v_pk_mul_f32 v[96:97], v[12:13], v[108:109]
	v_pk_mul_f32 v[102:103], v[10:11], v[106:107]
	v_pk_mul_f32 v[100:101], v[8:9], v[104:105]
	v_pk_mul_f32 v[106:107], v[6:7], v[120:121]
	v_pk_mul_f32 v[104:105], v[4:5], v[118:119]
	v_pk_mul_f32 v[110:111], v[2:3], v[116:117]
	v_pk_mul_f32 v[108:109], v[0:1], v[122:123]
	global_store_dwordx4 v[112:113], v[96:99], off
	global_store_dwordx4 v[112:113], v[100:103], off offset:64
	global_store_dwordx4 v[112:113], v[104:107], off offset:512
	global_store_dwordx4 v[112:113], v[108:111], off offset:576
	global_load_dwordx4 v[96:99], v[114:115], off
	s_nop 0
	global_load_dwordx4 v[100:103], v[114:115], off offset:16
	global_load_dwordx4 v[104:107], v[114:115], off offset:32
	global_load_dwordx4 v[108:111], v[114:115], off offset:48
	s_waitcnt vmcnt(2)
	v_pk_add_f32 v[98:99], v[98:99], v[102:103]
	v_pk_add_f32 v[96:97], v[96:97], v[100:101]
	s_waitcnt vmcnt(0)
	v_pk_add_f32 v[100:101], v[106:107], v[110:111]
	v_pk_add_f32 v[102:103], v[104:105], v[108:109]
	v_pk_add_f32 v[98:99], v[98:99], v[100:101]
	v_pk_add_f32 v[96:97], v[96:97], v[102:103]
	s_nop 0
	v_pk_mov_b32 v[100:101], v[96:97], v[98:99] op_sel:[1,0]
	v_mov_b32_e32 v97, v99
	v_pk_add_f32 v[96:97], v[100:101], v[96:97]
	v_lshl_add_u64 v[98:99], s[0:1], 0, v[180:181]
	v_add_f32_e32 v96, v96, v97
	v_fmamk_f32 v96, v96, 0x3a800000, v134
	v_mul_f32_e32 v97, 0x4b800000, v96
	v_cmp_gt_f32_e32 vcc, s2, v96
	s_nop 1
	v_cndmask_b32_e32 v96, v96, v97, vcc
	v_rsq_f32_e32 v100, v96
	v_lshl_add_u64 v[96:97], s[76:77], 0, v[150:151]
	v_lshl_add_u64 v[96:97], v[96:97], 0, v[144:145]
	v_mul_f32_e32 v101, 0x45800000, v100
	v_cndmask_b32_e32 v100, v100, v101, vcc
	v_pk_mul_f32 v[92:93], v[92:93], v[100:101] op_sel_hi:[1,0]
	v_pk_mul_f32 v[94:95], v[94:95], v[100:101] op_sel_hi:[1,0]
	v_pk_mul_f32 v[88:89], v[88:89], v[100:101] op_sel_hi:[1,0]
	v_pk_mul_f32 v[90:91], v[90:91], v[100:101] op_sel_hi:[1,0]
	v_pk_mul_f32 v[102:103], v[84:85], v[100:101] op_sel_hi:[1,0]
	v_pk_mul_f32 v[104:105], v[86:87], v[100:101] op_sel_hi:[1,0]
	v_pk_mul_f32 v[106:107], v[80:81], v[100:101] op_sel_hi:[1,0]
	v_pk_mul_f32 v[100:101], v[82:83], v[100:101] op_sel_hi:[1,0]
	v_pk_mul_f32 v[82:83], v[14:15], v[94:95]
	v_pk_mul_f32 v[80:81], v[12:13], v[92:93]
	v_pk_mul_f32 v[86:87], v[10:11], v[90:91]
	v_pk_mul_f32 v[84:85], v[8:9], v[88:89]
	v_pk_mul_f32 v[90:91], v[6:7], v[104:105]
	v_pk_mul_f32 v[88:89], v[4:5], v[102:103]
	v_pk_mul_f32 v[94:95], v[2:3], v[100:101]
	v_pk_mul_f32 v[92:93], v[0:1], v[106:107]
	global_store_dwordx4 v[96:97], v[80:83], off
	global_store_dwordx4 v[96:97], v[84:87], off offset:64
	global_store_dwordx4 v[96:97], v[88:91], off offset:512
	global_store_dwordx4 v[96:97], v[92:95], off offset:576
	global_load_dwordx4 v[80:83], v[98:99], off
	s_nop 0
	global_load_dwordx4 v[84:87], v[98:99], off offset:16
	global_load_dwordx4 v[88:91], v[98:99], off offset:32
	global_load_dwordx4 v[92:95], v[98:99], off offset:48
	s_waitcnt vmcnt(2)
	v_pk_add_f32 v[82:83], v[82:83], v[86:87]
	v_pk_add_f32 v[80:81], v[80:81], v[84:85]
	s_waitcnt vmcnt(0)
	v_pk_add_f32 v[84:85], v[90:91], v[94:95]
	v_pk_add_f32 v[86:87], v[88:89], v[92:93]
	v_pk_add_f32 v[82:83], v[82:83], v[84:85]
	v_pk_add_f32 v[80:81], v[80:81], v[86:87]
	s_nop 0
	v_pk_mov_b32 v[84:85], v[80:81], v[82:83] op_sel:[1,0]
	v_mov_b32_e32 v81, v83
	v_pk_add_f32 v[80:81], v[84:85], v[80:81]
	v_lshl_add_u64 v[82:83], s[0:1], 0, v[182:183]
	v_add_f32_e32 v80, v80, v81
	v_fmamk_f32 v80, v80, 0x3a800000, v134
	v_mul_f32_e32 v81, 0x4b800000, v80
	v_cmp_gt_f32_e32 vcc, s2, v80
	s_nop 1
	v_cndmask_b32_e32 v80, v80, v81, vcc
	v_rsq_f32_e32 v84, v80
	v_lshl_add_u64 v[80:81], s[76:77], 0, v[152:153]
	v_lshl_add_u64 v[80:81], v[80:81], 0, v[144:145]
	v_mul_f32_e32 v85, 0x45800000, v84
	v_cndmask_b32_e32 v84, v84, v85, vcc
	v_pk_mul_f32 v[76:77], v[76:77], v[84:85] op_sel_hi:[1,0]
	v_pk_mul_f32 v[78:79], v[78:79], v[84:85] op_sel_hi:[1,0]
	v_pk_mul_f32 v[72:73], v[72:73], v[84:85] op_sel_hi:[1,0]
	v_pk_mul_f32 v[74:75], v[74:75], v[84:85] op_sel_hi:[1,0]
	v_pk_mul_f32 v[86:87], v[68:69], v[84:85] op_sel_hi:[1,0]
	v_pk_mul_f32 v[88:89], v[70:71], v[84:85] op_sel_hi:[1,0]
	v_pk_mul_f32 v[90:91], v[64:65], v[84:85] op_sel_hi:[1,0]
	v_pk_mul_f32 v[84:85], v[66:67], v[84:85] op_sel_hi:[1,0]
	v_pk_mul_f32 v[66:67], v[14:15], v[78:79]
	v_pk_mul_f32 v[64:65], v[12:13], v[76:77]
	v_pk_mul_f32 v[70:71], v[10:11], v[74:75]
	v_pk_mul_f32 v[68:69], v[8:9], v[72:73]
	v_pk_mul_f32 v[74:75], v[6:7], v[88:89]
	v_pk_mul_f32 v[72:73], v[4:5], v[86:87]
	v_pk_mul_f32 v[78:79], v[2:3], v[84:85]
	v_pk_mul_f32 v[76:77], v[0:1], v[90:91]
	global_store_dwordx4 v[80:81], v[64:67], off
	global_store_dwordx4 v[80:81], v[68:71], off offset:64
	global_store_dwordx4 v[80:81], v[72:75], off offset:512
	global_store_dwordx4 v[80:81], v[76:79], off offset:576
	global_load_dwordx4 v[64:67], v[82:83], off
	s_nop 0
	global_load_dwordx4 v[68:71], v[82:83], off offset:16
	global_load_dwordx4 v[72:75], v[82:83], off offset:32
	global_load_dwordx4 v[76:79], v[82:83], off offset:48
	s_waitcnt vmcnt(2)
	v_pk_add_f32 v[66:67], v[66:67], v[70:71]
	v_pk_add_f32 v[64:65], v[64:65], v[68:69]
	s_waitcnt vmcnt(0)
	v_pk_add_f32 v[68:69], v[74:75], v[78:79]
	v_pk_add_f32 v[70:71], v[72:73], v[76:77]
	v_pk_add_f32 v[66:67], v[66:67], v[68:69]
	v_pk_add_f32 v[64:65], v[64:65], v[70:71]
	s_nop 0
	v_pk_mov_b32 v[68:69], v[64:65], v[66:67] op_sel:[1,0]
	v_mov_b32_e32 v65, v67
	v_pk_add_f32 v[64:65], v[68:69], v[64:65]
	v_lshl_add_u64 v[66:67], s[0:1], 0, v[184:185]
	v_add_f32_e32 v64, v64, v65
	v_fmamk_f32 v64, v64, 0x3a800000, v134
	v_mul_f32_e32 v65, 0x4b800000, v64
	v_cmp_gt_f32_e32 vcc, s2, v64
	s_nop 1
	v_cndmask_b32_e32 v64, v64, v65, vcc
	v_rsq_f32_e32 v68, v64
	v_lshl_add_u64 v[64:65], s[76:77], 0, v[154:155]
	v_lshl_add_u64 v[64:65], v[64:65], 0, v[144:145]
	v_mul_f32_e32 v69, 0x45800000, v68
	v_cndmask_b32_e32 v68, v68, v69, vcc
	v_pk_mul_f32 v[60:61], v[60:61], v[68:69] op_sel_hi:[1,0]
	v_pk_mul_f32 v[62:63], v[62:63], v[68:69] op_sel_hi:[1,0]
	v_pk_mul_f32 v[56:57], v[56:57], v[68:69] op_sel_hi:[1,0]
	v_pk_mul_f32 v[58:59], v[58:59], v[68:69] op_sel_hi:[1,0]
	v_pk_mul_f32 v[70:71], v[52:53], v[68:69] op_sel_hi:[1,0]
	v_pk_mul_f32 v[72:73], v[54:55], v[68:69] op_sel_hi:[1,0]
	v_pk_mul_f32 v[74:75], v[48:49], v[68:69] op_sel_hi:[1,0]
	v_pk_mul_f32 v[68:69], v[50:51], v[68:69] op_sel_hi:[1,0]
	v_pk_mul_f32 v[50:51], v[14:15], v[62:63]
	v_pk_mul_f32 v[48:49], v[12:13], v[60:61]
	v_pk_mul_f32 v[54:55], v[10:11], v[58:59]
	v_pk_mul_f32 v[52:53], v[8:9], v[56:57]
	v_pk_mul_f32 v[58:59], v[6:7], v[72:73]
	v_pk_mul_f32 v[56:57], v[4:5], v[70:71]
	v_pk_mul_f32 v[62:63], v[2:3], v[68:69]
	v_pk_mul_f32 v[60:61], v[0:1], v[74:75]
	global_store_dwordx4 v[64:65], v[48:51], off
	global_store_dwordx4 v[64:65], v[52:55], off offset:64
	global_store_dwordx4 v[64:65], v[56:59], off offset:512
	global_store_dwordx4 v[64:65], v[60:63], off offset:576
	global_load_dwordx4 v[48:51], v[66:67], off
	s_nop 0
	global_load_dwordx4 v[52:55], v[66:67], off offset:16
	global_load_dwordx4 v[56:59], v[66:67], off offset:32
	global_load_dwordx4 v[60:63], v[66:67], off offset:48
	s_waitcnt vmcnt(2)
	v_pk_add_f32 v[50:51], v[50:51], v[54:55]
	v_pk_add_f32 v[48:49], v[48:49], v[52:53]
	s_waitcnt vmcnt(0)
	v_pk_add_f32 v[52:53], v[58:59], v[62:63]
	v_pk_add_f32 v[54:55], v[56:57], v[60:61]
	v_pk_add_f32 v[50:51], v[50:51], v[52:53]
	v_pk_add_f32 v[48:49], v[48:49], v[54:55]
	s_nop 0
	v_pk_mov_b32 v[52:53], v[48:49], v[50:51] op_sel:[1,0]
	v_mov_b32_e32 v49, v51
	v_pk_add_f32 v[48:49], v[52:53], v[48:49]
	v_lshl_add_u64 v[50:51], s[0:1], 0, v[186:187]
	v_add_f32_e32 v48, v48, v49
	v_fmamk_f32 v48, v48, 0x3a800000, v134
	v_mul_f32_e32 v49, 0x4b800000, v48
	v_cmp_gt_f32_e32 vcc, s2, v48
	s_nop 1
	v_cndmask_b32_e32 v48, v48, v49, vcc
	v_rsq_f32_e32 v52, v48
	v_lshl_add_u64 v[48:49], s[76:77], 0, v[156:157]
	v_lshl_add_u64 v[48:49], v[48:49], 0, v[144:145]
	v_mul_f32_e32 v53, 0x45800000, v52
	v_cndmask_b32_e32 v52, v52, v53, vcc
	v_pk_mul_f32 v[44:45], v[44:45], v[52:53] op_sel_hi:[1,0]
	v_pk_mul_f32 v[46:47], v[46:47], v[52:53] op_sel_hi:[1,0]
	v_pk_mul_f32 v[40:41], v[40:41], v[52:53] op_sel_hi:[1,0]
	v_pk_mul_f32 v[42:43], v[42:43], v[52:53] op_sel_hi:[1,0]
	v_pk_mul_f32 v[54:55], v[36:37], v[52:53] op_sel_hi:[1,0]
	v_pk_mul_f32 v[56:57], v[38:39], v[52:53] op_sel_hi:[1,0]
	v_pk_mul_f32 v[58:59], v[32:33], v[52:53] op_sel_hi:[1,0]
	v_pk_mul_f32 v[52:53], v[34:35], v[52:53] op_sel_hi:[1,0]
	v_pk_mul_f32 v[34:35], v[14:15], v[46:47]
	v_pk_mul_f32 v[32:33], v[12:13], v[44:45]
	v_pk_mul_f32 v[38:39], v[10:11], v[42:43]
	v_pk_mul_f32 v[36:37], v[8:9], v[40:41]
	v_pk_mul_f32 v[42:43], v[6:7], v[56:57]
	v_pk_mul_f32 v[40:41], v[4:5], v[54:55]
	v_pk_mul_f32 v[46:47], v[2:3], v[52:53]
	v_pk_mul_f32 v[44:45], v[0:1], v[58:59]
	global_store_dwordx4 v[48:49], v[32:35], off
	global_store_dwordx4 v[48:49], v[36:39], off offset:64
	global_store_dwordx4 v[48:49], v[40:43], off offset:512
	global_store_dwordx4 v[48:49], v[44:47], off offset:576
	global_load_dwordx4 v[32:35], v[50:51], off
	s_nop 0
	global_load_dwordx4 v[36:39], v[50:51], off offset:16
	global_load_dwordx4 v[40:43], v[50:51], off offset:32
	global_load_dwordx4 v[44:47], v[50:51], off offset:48
	s_waitcnt vmcnt(2)
	v_pk_add_f32 v[34:35], v[34:35], v[38:39]
	v_pk_add_f32 v[32:33], v[32:33], v[36:37]
	s_waitcnt vmcnt(0)
	v_pk_add_f32 v[36:37], v[42:43], v[46:47]
	v_pk_add_f32 v[38:39], v[40:41], v[44:45]
	v_pk_add_f32 v[34:35], v[34:35], v[36:37]
	v_pk_add_f32 v[32:33], v[32:33], v[38:39]
	v_lshl_add_u64 v[44:45], s[0:1], 0, v[132:133]
	v_pk_mov_b32 v[36:37], v[32:33], v[34:35] op_sel:[1,0]
	v_mov_b32_e32 v33, v35
	v_pk_add_f32 v[32:33], v[36:37], v[32:33]
	s_movk_i32 s0, 0x80
	v_add_f32_e32 v32, v32, v33
	v_fmamk_f32 v32, v32, 0x3a800000, v134
	v_mul_f32_e32 v33, 0x4b800000, v32
	v_cmp_gt_f32_e32 vcc, s2, v32
	s_nop 1
	v_cndmask_b32_e32 v32, v32, v33, vcc
	v_rsq_f32_e32 v34, v32
	v_lshl_add_u64 v[32:33], s[76:77], 0, v[158:159]
	v_lshl_add_u64 v[46:47], v[32:33], 0, v[144:145]
	v_mul_f32_e32 v32, 0x45800000, v34
	v_cndmask_b32_e32 v32, v34, v32, vcc
	v_pk_mul_f32 v[34:35], v[166:167], v[32:33] op_sel_hi:[1,0]
	v_pk_mul_f32 v[36:37], v[160:161], v[32:33] op_sel_hi:[1,0]
	v_pk_mul_f32 v[38:39], v[164:165], v[32:33] op_sel_hi:[1,0]
	v_pk_mul_f32 v[40:41], v[30:31], v[32:33] op_sel_hi:[1,0]
	v_pk_mul_f32 v[42:43], v[162:163], v[32:33] op_sel_hi:[1,0]
	v_pk_mul_f32 v[48:49], v[28:29], v[32:33] op_sel_hi:[1,0]
	v_pk_mul_f32 v[50:51], v[170:171], v[32:33] op_sel_hi:[1,0]
	v_pk_mul_f32 v[52:53], v[168:169], v[32:33] op_sel_hi:[1,0]
	v_pk_mul_f32 v[30:31], v[14:15], v[36:37]
	v_pk_mul_f32 v[28:29], v[12:13], v[34:35]
	v_pk_mul_f32 v[34:35], v[10:11], v[40:41]
	v_pk_mul_f32 v[32:33], v[8:9], v[38:39]
	v_pk_mul_f32 v[38:39], v[6:7], v[48:49]
	v_pk_mul_f32 v[36:37], v[4:5], v[42:43]
	v_pk_mul_f32 v[42:43], v[2:3], v[52:53]
	v_pk_mul_f32 v[40:41], v[0:1], v[50:51]
	global_store_dwordx4 v[46:47], v[28:31], off
	global_store_dwordx4 v[46:47], v[32:35], off offset:64
	global_store_dwordx4 v[46:47], v[36:39], off offset:512
	global_store_dwordx4 v[46:47], v[40:43], off offset:576
	global_load_dwordx4 v[28:31], v[44:45], off
	s_nop 0
	global_load_dwordx4 v[32:35], v[44:45], off offset:16
	global_load_dwordx4 v[36:39], v[44:45], off offset:32
	global_load_dwordx4 v[40:43], v[44:45], off offset:48
	v_lshl_add_u64 v[44:45], s[76:77], 0, v[172:173]
	s_waitcnt vmcnt(2)
	v_pk_add_f32 v[30:31], v[30:31], v[34:35]
	v_pk_add_f32 v[28:29], v[28:29], v[32:33]
	s_waitcnt vmcnt(0)
	v_pk_add_f32 v[32:33], v[38:39], v[42:43]
	v_pk_add_f32 v[34:35], v[36:37], v[40:41]
	v_pk_add_f32 v[30:31], v[30:31], v[32:33]
	v_pk_add_f32 v[28:29], v[28:29], v[34:35]
	s_nop 0
	v_pk_mov_b32 v[32:33], v[28:29], v[30:31] op_sel:[1,0]
	v_mov_b32_e32 v29, v31
	v_pk_add_f32 v[28:29], v[32:33], v[28:29]
	v_lshl_add_u64 v[30:31], v[44:45], 0, v[144:145]
	v_add_f32_e32 v28, v28, v29
	v_fmamk_f32 v28, v28, 0x3a800000, v134
	v_mul_f32_e32 v29, 0x4b800000, v28
	v_cmp_gt_f32_e32 vcc, s2, v28
	s_nop 1
	v_cndmask_b32_e32 v28, v28, v29, vcc
	v_rsq_f32_e32 v29, v28
	v_lshl_add_u32 v28, s92, 3, v190
	v_mul_f32_e32 v32, 0x45800000, v29
	v_cndmask_b32_e32 v32, v29, v32, vcc
	v_pk_mul_f32 v[26:27], v[26:27], v[32:33] op_sel_hi:[1,0]
	v_pk_mul_f32 v[20:21], v[20:21], v[32:33] op_sel_hi:[1,0]
	v_pk_mul_f32 v[24:25], v[24:25], v[32:33] op_sel_hi:[1,0]
	v_pk_mul_f32 v[18:19], v[18:19], v[32:33] op_sel_hi:[1,0]
	v_pk_mul_f32 v[22:23], v[22:23], v[32:33] op_sel_hi:[1,0]
	v_pk_mul_f32 v[16:17], v[16:17], v[32:33] op_sel_hi:[1,0]
	v_pk_mul_f32 v[34:35], v[130:131], v[32:33] op_sel_hi:[1,0]
	v_pk_mul_f32 v[32:33], v[128:129], v[32:33] op_sel_hi:[1,0]
	v_pk_mul_f32 v[14:15], v[14:15], v[20:21]
	v_pk_mul_f32 v[12:13], v[12:13], v[26:27]
	v_cmp_gt_i32_e32 vcc, s0, v28
	v_pk_mul_f32 v[10:11], v[10:11], v[18:19]
	v_pk_mul_f32 v[8:9], v[8:9], v[24:25]
	v_pk_mul_f32 v[6:7], v[6:7], v[16:17]
	v_pk_mul_f32 v[4:5], v[4:5], v[22:23]
	v_pk_mul_f32 v[2:3], v[2:3], v[32:33]
	v_pk_mul_f32 v[0:1], v[0:1], v[34:35]
	global_store_dwordx4 v[30:31], v[12:15], off
	global_store_dwordx4 v[30:31], v[8:11], off offset:64
	global_store_dwordx4 v[30:31], v[4:7], off offset:512
	global_store_dwordx4 v[30:31], v[0:3], off offset:576
	s_and_saveexec_b64 s[0:1], vcc
	s_cbranch_execz .LBB0_974
	v_ashrrev_i32_e32 v29, 31, v28
	v_lshlrev_b64 v[20:21], 12, v[28:29]
	v_lshlrev_b32_e32 v22, 4, v191
	v_mov_b32_e32 v23, 0
	v_lshl_add_u64 v[20:21], s[76:77], 0, v[20:21]
	v_lshl_add_u64 v[20:21], v[20:21], 0, v[22:23]
	s_brev_b32 s0, 32
	v_mov_b32_e32 v0, v216
	v_mov_b32_e32 v1, v217
	v_mov_b32_e32 v2, v218
	v_mov_b32_e32 v3, v219
	v_mov_b32_e32 v4, v220
	v_mov_b32_e32 v5, v221
	v_mov_b32_e32 v6, v222
	v_mov_b32_e32 v7, v223
	v_mov_b32_e32 v8, v224
	v_mov_b32_e32 v9, v225
	v_mov_b32_e32 v10, v226
	v_mov_b32_e32 v11, v227
	v_mov_b32_e32 v12, v228
	v_mov_b32_e32 v13, v229
	v_mov_b32_e32 v14, v230
	v_mov_b32_e32 v15, v231
	v_mov_b32_e32 v16, v236
	v_mov_b32_e32 v17, v237
	v_mov_b32_e32 v18, v238
	v_mov_b32_e32 v19, v239
	v_pk_mul_f32 v[24:25], v[2:3], v[2:3]
	v_pk_mul_f32 v[26:27], v[0:1], v[0:1]
	v_mul_f32_e32 v28, v5, v5
	v_mul_f32_e32 v30, v7, v7
	v_pk_mul_f32 v[32:33], v[10:11], v[10:11]
	v_pk_mul_f32 v[34:35], v[8:9], v[8:9]
	v_pk_mov_b32 v[36:37], v[26:27], v[24:25] op_sel:[1,0]
	v_mov_b32_e32 v27, v25
	v_mul_f32_e32 v40, v14, v14
	v_mul_f32_e32 v41, v15, v15
	v_pk_fma_f32 v[24:25], v[4:5], v[4:5], v[28:29] op_sel_hi:[1,1,0]
	v_pk_fma_f32 v[28:29], v[6:7], v[6:7], v[30:31] op_sel_hi:[1,1,0]
	v_pk_mov_b32 v[30:31], v[34:35], v[32:33] op_sel:[1,0]
	v_mov_b32_e32 v35, v33
	v_pk_add_f32 v[26:27], v[36:37], v[26:27]
	v_mov_b32_e32 v25, v40
	v_mov_b32_e32 v29, v41
	v_pk_add_f32 v[30:31], v[30:31], v[34:35]
	v_mul_f32_e32 v38, v12, v12
	v_mul_f32_e32 v39, v13, v13
	v_pk_add_f32 v[26:27], v[26:27], v[26:27] op_sel:[0,1] op_sel_hi:[1,0]
	v_pk_add_f32 v[24:25], v[24:25], v[28:29]
	v_pk_add_f32 v[28:29], v[30:31], v[30:31] op_sel:[0,1] op_sel_hi:[1,0]
	v_mov_b32_e32 v27, v39
	v_mov_b32_e32 v29, v38
	v_pk_add_f32 v[26:27], v[28:29], v[26:27]
	s_nop 0
	v_pk_add_f32 v[24:25], v[26:27], v[24:25]
	s_nop 0
	v_add_f32_e32 v24, v24, v25
	ds_bpermute_b32 v25, v203, v24
	s_waitcnt lgkmcnt(0)
	v_add_f32_e32 v24, v24, v25
	ds_bpermute_b32 v25, v204, v24
	s_waitcnt lgkmcnt(0)
	v_add_f32_e32 v24, v24, v25
	ds_bpermute_b32 v25, v205, v24
	s_waitcnt lgkmcnt(0)
	v_add_f32_e32 v24, v24, v25
	ds_bpermute_b32 v25, v206, v24
	s_waitcnt lgkmcnt(0)
	v_add_f32_e32 v24, v24, v25
	ds_bpermute_b32 v25, v207, v24
	s_waitcnt lgkmcnt(0)
	v_add_f32_e32 v24, v24, v25
	ds_bpermute_b32 v25, v208, v24
	s_waitcnt lgkmcnt(0)
	v_add_f32_e32 v23, v24, v25
	v_fmac_f32_e32 v134, 0x3a800000, v23
	v_mul_f32_e32 v23, 0x4b800000, v134
	v_cmp_gt_f32_e32 vcc, s2, v134
	v_add_co_u32_e64 v24, s[0:1], s0, v20
	s_nop 0
	v_cndmask_b32_e32 v23, v134, v23, vcc
	v_rsq_f32_e32 v23, v23
	v_addc_co_u32_e64 v25, s[0:1], 0, v21, s[0:1]
	s_mov_b64 s[0:1], 0x4000000
	v_mul_f32_e32 v26, 0x45800000, v23
	v_cndmask_b32_e32 v26, v23, v26, vcc
	v_pk_mul_f32 v[8:9], v[8:9], v[26:27] op_sel_hi:[1,0]
	v_pk_mul_f32 v[10:11], v[10:11], v[26:27] op_sel_hi:[1,0]
	v_pk_mul_f32 v[8:9], v[16:17], v[8:9]
	v_pk_mul_f32 v[10:11], v[18:19], v[10:11]
	global_store_dwordx4 v[24:25], v[8:11], off
	v_pk_mul_f32 v[2:3], v[2:3], v[26:27] op_sel_hi:[1,0]
	v_pk_mul_f32 v[0:1], v[0:1], v[26:27] op_sel_hi:[1,0]
	v_lshl_add_u64 v[16:17], v[20:21], 0, s[0:1]
	v_pk_mul_f32 v[6:7], v[6:7], v[26:27] op_sel_hi:[1,0]
	v_pk_mul_f32 v[4:5], v[4:5], v[26:27] op_sel_hi:[1,0]
	v_pk_mul_f32 v[0:1], v[240:241], v[0:1]
	v_pk_mul_f32 v[2:3], v[242:243], v[2:3]
	global_store_dwordx4 v[16:17], v[0:3], off offset:1024
	v_pk_mul_f32 v[32:33], v[244:245], v[4:5]
	v_pk_mul_f32 v[34:35], v[246:247], v[6:7]
	global_store_dwordx4 v[16:17], v[32:35], off offset:2048
	v_pk_mul_f32 v[4:5], v[14:15], v[26:27] op_sel_hi:[1,0]
	v_pk_mul_f32 v[6:7], v[12:13], v[26:27] op_sel_hi:[1,0]
	v_pk_mul_f32 v[38:39], v[250:251], v[4:5]
	v_pk_mul_f32 v[36:37], v[248:249], v[6:7]
	global_store_dwordx4 v[16:17], v[36:39], off offset:3072

	.amdhsa_kernel _Z10fwd_kernel4Args
		.amdhsa_group_segment_fixed_size 0
		.amdhsa_private_segment_fixed_size 0
		.amdhsa_kernarg_size 432
		.amdhsa_user_sgpr_count 2
		.amdhsa_user_sgpr_dispatch_ptr 0
		.amdhsa_user_sgpr_queue_ptr 0
		.amdhsa_user_sgpr_kernarg_segment_ptr 1
		.amdhsa_user_sgpr_dispatch_id 0
		.amdhsa_user_sgpr_kernarg_preload_length 0
		.amdhsa_user_sgpr_kernarg_preload_offset 0
		.amdhsa_user_sgpr_private_segment_size 0
		.amdhsa_uses_dynamic_stack 0
		.amdhsa_enable_private_segment 0
		.amdhsa_system_sgpr_workgroup_id_x 1
		.amdhsa_system_sgpr_workgroup_id_y 0
		.amdhsa_system_sgpr_workgroup_id_z 0
		.amdhsa_system_sgpr_workgroup_info 0
		.amdhsa_system_vgpr_workitem_id 2
		.amdhsa_next_free_vgpr 252
		.amdhsa_next_free_sgpr 102
		.amdhsa_accum_offset 252
		.amdhsa_reserve_vcc 1
		.amdhsa_float_round_mode_32 0
		.amdhsa_float_round_mode_16_64 0
		.amdhsa_float_denorm_mode_32 3
		.amdhsa_float_denorm_mode_16_64 3
		.amdhsa_dx10_clamp 1
		.amdhsa_ieee_mode 1
		.amdhsa_fp16_overflow 0
		.amdhsa_tg_split 0
		.amdhsa_exception_fp_ieee_invalid_op 0
		.amdhsa_exception_fp_denorm_src 0
		.amdhsa_exception_fp_ieee_div_zero 0
		.amdhsa_exception_fp_ieee_overflow 0
		.amdhsa_exception_fp_ieee_underflow 0
		.amdhsa_exception_fp_ieee_inexact 0
		.amdhsa_exception_int_div_zero 0
	.end_amdhsa_kernel

amdhsa.kernels:
  - .agpr_count:     0
    .args:
      - .offset:         0
        .size:           176
        .value_kind:     by_value
      - .offset:         176
        .size:           4
        .value_kind:     hidden_block_count_x
      - .offset:         180
        .size:           4
        .value_kind:     hidden_block_count_y
      - .offset:         184
        .size:           4
        .value_kind:     hidden_block_count_z
      - .offset:         188
        .size:           2
        .value_kind:     hidden_group_size_x
      - .offset:         190
        .size:           2
        .value_kind:     hidden_group_size_y
      - .offset:         192
        .size:           2
        .value_kind:     hidden_group_size_z
      - .offset:         194
        .size:           2
        .value_kind:     hidden_remainder_x
      - .offset:         196
        .size:           2
        .value_kind:     hidden_remainder_y
      - .offset:         198
        .size:           2
        .value_kind:     hidden_remainder_z
      - .offset:         216
        .size:           8
        .value_kind:     hidden_global_offset_x
      - .offset:         224
        .size:           8
        .value_kind:     hidden_global_offset_y
      - .offset:         232
        .size:           8
        .value_kind:     hidden_global_offset_z
      - .offset:         240
        .size:           2
        .value_kind:     hidden_grid_dims
      - .offset:         264
        .size:           8
        .value_kind:     hidden_multigrid_sync_arg
      - .offset:         296
        .size:           4
        .value_kind:     hidden_dynamic_lds_size
    .group_segment_fixed_size: 0
    .kernarg_segment_align: 8
    .kernarg_segment_size: 432
    .language:       OpenCL C
    .language_version:
      - 2
      - 0
    .max_flat_workgroup_size: 512
    .name:           _Z10fwd_kernel4Args
    .private_segment_fixed_size: 0
    .sgpr_count:     108
    .sgpr_spill_count: 51
    .symbol:         _Z10fwd_kernel4Args.kd
    .uniform_work_group_size: 1
    .uses_dynamic_stack: false
    .vgpr_count:     252
    .vgpr_spill_count: 0
    .wavefront_size: 64
